# all mixa/P4/P7-epilogue edits plus grid barrier: non-leader workgroups poll the cross-XCD generation word directly (one hop fewer on release)
# baseline (speedup 1.0000x reference)
; __device__ __forceinline__ unsigned xb_ld(unsigned* p)              { return __hip_atomic_load(p, __ATOMIC_RELAXED, __HIP_MEMORY_SCOPE_AGENT); }
; __device__ __forceinline__ unsigned xb_add(unsigned* p, unsigned v) { return __hip_atomic_fetch_add(p, v, __ATOMIC_RELAXED, __HIP_MEMORY_SCOPE_AGENT); }
; #define XB_SPIN(cond, bar) do { unsigned _sp = 0; while (cond) { __builtin_amdgcn_s_sleep(1); \
;     if ((++_sp & 255u) == 0u) { if (xb_ld(&(bar)[XB_TMO])) break; if (_sp > XB_SPIN_CAP) { atomicAdd(&(bar)[XB_TMO], 1u); break; } } } } while (0)
; __device__ __forceinline__ void xcd_barrier(const XcdBarrier& b) {
;     ...
;         const unsigned old = xb_add(&bar[XB_XSUB(b.x)], 1u);
;         const unsigned gen = old / nloc;
;         if (old + 1u == (gen + 1u) * nloc) {
;             __builtin_amdgcn_fence(__ATOMIC_RELEASE, "agent");
;             asm volatile("s_waitcnt vmcnt(0)" ::: "memory");
;             const unsigned og = xb_add(&bar[XB_TOP], 1u);
;             const unsigned tg = og / nx;
;             if (og + 1u == (tg + 1u) * nx) xb_add(&bar[XB_TOPGEN], 1u);
;             else XB_SPIN(xb_ld(&bar[XB_TOPGEN]) == tg, bar);
;             __builtin_amdgcn_fence(__ATOMIC_ACQUIRE, "agent");
;             xb_add(&bar[XB_XGEN(b.x)], 1u);
;             asm volatile("s_waitcnt vmcnt(0)" ::: "memory");
;         } else {
;             XB_SPIN(xb_ld(&bar[XB_XGEN(b.x)]) == gen, bar);
.LBB0_245:
	s_or_b64 exec, exec, s[8:9]
	v_cvt_f32_u32_e32 v5, v3
	s_waitcnt vmcnt(0)
	v_readfirstlane_b32 s3, v4
	v_sub_u32_e32 v4, 0, v3
	v_rcp_iflag_f32_e32 v5, v5
	v_add_u32_e32 v6, s3, v1
	v_mul_f32_e32 v5, 0x4f7ffffe, v5
	v_cvt_u32_f32_e32 v5, v5
	v_mul_lo_u32 v1, v4, v5
	v_mul_hi_u32 v1, v5, v1
	v_add_u32_e32 v1, v5, v1
	v_mul_hi_u32 v1, v6, v1
	v_mul_lo_u32 v4, v1, v3
	v_sub_u32_e32 v4, v6, v4
	v_add_u32_e32 v5, 1, v1
	v_cmp_ge_u32_e32 vcc, v4, v3
	s_nop 1
	v_cndmask_b32_e32 v1, v1, v5, vcc
	v_sub_u32_e32 v5, v4, v3
	v_cndmask_b32_e32 v4, v4, v5, vcc
	v_add_u32_e32 v5, 1, v1
	v_cmp_ge_u32_e32 vcc, v4, v3
	v_add_u32_e32 v4, 1, v6
	s_nop 0
	v_cndmask_b32_e32 v1, v1, v5, vcc
	v_mul_lo_u32 v5, v3, v1
	v_add_u32_e32 v3, v5, v3
	v_cmp_ne_u32_e32 vcc, v4, v3
	s_and_saveexec_b64 s[8:9], vcc
	s_xor_b64 s[8:9], exec, s[8:9]
	s_cbranch_execz .LBB0_259
	v_readlane_b32 s10, v253, 43
	v_readlane_b32 s11, v253, 44
	s_waitcnt lgkmcnt(0)
	s_nop 3
	global_load_dword v2, v114, s[10:11] sc1
	s_waitcnt vmcnt(0)
	v_cmp_eq_u32_e32 vcc, v2, v1
	s_and_saveexec_b64 s[10:11], vcc
	s_cbranch_execz .LBB0_258
	s_mov_b32 s3, 1
	s_mov_b64 s[12:13], 0
	s_branch .LBB0_249

; __device__ __forceinline__ unsigned xb_ld(unsigned* p)              { return __hip_atomic_load(p, __ATOMIC_RELAXED, __HIP_MEMORY_SCOPE_AGENT); }
; __device__ __forceinline__ unsigned xb_add(unsigned* p, unsigned v) { return __hip_atomic_fetch_add(p, v, __ATOMIC_RELAXED, __HIP_MEMORY_SCOPE_AGENT); }
; #define XB_SPIN(cond, bar) do { unsigned _sp = 0; while (cond) { __builtin_amdgcn_s_sleep(1); \
;     if ((++_sp & 255u) == 0u) { if (xb_ld(&(bar)[XB_TMO])) break; if (_sp > XB_SPIN_CAP) { atomicAdd(&(bar)[XB_TMO], 1u); break; } } } } while (0)
; __device__ __forceinline__ void xcd_barrier(const XcdBarrier& b) {
;     ...
;         const unsigned old = xb_add(&bar[XB_XSUB(b.x)], 1u);
;         const unsigned gen = old / nloc;
;         if (old + 1u == (gen + 1u) * nloc) {
;             __builtin_amdgcn_fence(__ATOMIC_RELEASE, "agent");
;             asm volatile("s_waitcnt vmcnt(0)" ::: "memory");
;             const unsigned og = xb_add(&bar[XB_TOP], 1u);
;             const unsigned tg = og / nx;
;             if (og + 1u == (tg + 1u) * nx) xb_add(&bar[XB_TOPGEN], 1u);
;             else XB_SPIN(xb_ld(&bar[XB_TOPGEN]) == tg, bar);
;             __builtin_amdgcn_fence(__ATOMIC_ACQUIRE, "agent");
;             xb_add(&bar[XB_XGEN(b.x)], 1u);
;             asm volatile("s_waitcnt vmcnt(0)" ::: "memory");
;         } else {
;             XB_SPIN(xb_ld(&bar[XB_XGEN(b.x)]) == gen, bar);
.LBB0_819:
	s_or_b64 exec, exec, s[8:9]
	v_cvt_f32_u32_e32 v5, v3
	s_waitcnt vmcnt(0)
	v_readfirstlane_b32 s2, v4
	v_sub_u32_e32 v4, 0, v3
	v_rcp_iflag_f32_e32 v5, v5
	v_add_u32_e32 v6, s2, v1
	v_mul_f32_e32 v5, 0x4f7ffffe, v5
	v_cvt_u32_f32_e32 v5, v5
	v_mul_lo_u32 v1, v4, v5
	v_mul_hi_u32 v1, v5, v1
	v_add_u32_e32 v1, v5, v1
	v_mul_hi_u32 v1, v6, v1
	v_mul_lo_u32 v4, v1, v3
	v_sub_u32_e32 v4, v6, v4
	v_add_u32_e32 v5, 1, v1
	v_cmp_ge_u32_e32 vcc, v4, v3
	s_nop 1
	v_cndmask_b32_e32 v1, v1, v5, vcc
	v_sub_u32_e32 v5, v4, v3
	v_cndmask_b32_e32 v4, v4, v5, vcc
	v_add_u32_e32 v5, 1, v1
	v_cmp_ge_u32_e32 vcc, v4, v3
	v_add_u32_e32 v4, 1, v6
	s_nop 0
	v_cndmask_b32_e32 v1, v1, v5, vcc
	v_mul_lo_u32 v5, v3, v1
	v_add_u32_e32 v3, v5, v3
	v_cmp_ne_u32_e32 vcc, v4, v3
	s_and_saveexec_b64 s[2:3], vcc
	s_xor_b64 s[8:9], exec, s[2:3]
	s_cbranch_execz .LBB0_833
	v_readlane_b32 s2, v253, 43
	v_readlane_b32 s3, v253, 44
	s_waitcnt lgkmcnt(0)
	s_nop 3
	global_load_dword v2, v114, s[2:3] sc1
	s_waitcnt vmcnt(0)
	v_cmp_eq_u32_e32 vcc, v2, v1
	s_and_saveexec_b64 s[10:11], vcc
	s_cbranch_execz .LBB0_832
	s_mov_b32 s2, 1
	s_mov_b64 s[12:13], 0
	s_branch .LBB0_823
